# dense attention (mixer C) by a hand-written kernel: two q-heads of a kv head per pass, K/V^T tiles by LDS-DMA into a swizzled 4-slot ring, packed-f32 online softmax; SSD-B blocks no longer take a dens
# speedup vs baseline: 1.0684x; 1.0043x over previous
.LBB0_883:
	s_andn2_b64 vcc, exec, s[6:7]
	s_cbranch_vccnz .LBB0_979
	s_cmpk_gt_i32 s40, 0x8f
	s_cbranch_scc0 .LBB0_893
	s_branch .Lga_entry
	v_mov_b32_e32 v2, s64
	v_mov_b32_e32 v3, s65
	v_mov_b32_e32 v4, s64
	v_readfirstlane_b32 s0, v2
	v_readfirstlane_b32 s1, v3
	v_mov_b32_e32 v5, s65
	v_mov_b32_e32 v2, s0
	v_mov_b32_e32 v3, s1
	global_load_dwordx2 v[2:3], v[2:3], off offset:248
	s_waitcnt vmcnt(0) lgkmcnt(0)
	v_mov_b32_e32 v0, s64
	v_readfirstlane_b32 s0, v4
	v_readfirstlane_b32 s1, v5
	v_mov_b32_e32 v6, s65
	v_mov_b32_e32 v4, s0
	v_mov_b32_e32 v5, s1
	global_load_dwordx2 v[4:5], v[4:5], off offset:248
	v_mov_b32_e32 v32, v247
	s_mov_b32 s15, s19
	s_mov_b32 s9, s19
	v_mov_b32_e32 v31, v1
	v_cmp_lt_i32_e32 vcc, v222, v220
	v_mov_b32_e32 v68, 0xf149f2ca
	v_mov_b32_e32 v64, 0
	s_waitcnt vmcnt(0) lgkmcnt(0)
	v_mov_b32_e32 v8, v5
	s_nop 0
	v_readfirstlane_b32 s0, v0
	v_readfirstlane_b32 s1, v6
	v_readfirstlane_b32 s20, v4
	v_mov_b32_e32 v6, s0
	v_readfirstlane_b32 s0, v2
	v_mov_b32_e32 v7, s1
	v_readfirstlane_b32 s1, v3
	s_add_u32 s12, s0, 0x9f00000
	global_load_dwordx2 v[50:51], v[6:7], off offset:248
	s_addc_u32 s13, s1, 0
	s_lshl_b32 s0, s40, 7
	s_lshr_b32 s18, s40, 6
	s_lshl_b32 s1, s40, 1
	s_and_b32 s0, s0, 0x780
	s_waitcnt vmcnt(0) lgkmcnt(0)
	s_lshl_b64 s[6:7], s[18:19], 11
	v_ashrrev_i32_e32 v0, 2, v32
	v_and_b32_e32 v33, 15, v32
	s_and_b32 s4, s1, 64
	s_lshl_b32 s1, s18, 8
	v_readfirstlane_b32 s21, v8
	v_lshrrev_b32_e32 v4, 1, v32
	v_ashrrev_i32_e32 v54, 3, v32
	v_and_b32_e32 v8, -16, v0
	v_or_b32_e32 v0, s0, v33
	v_mov_b32_e32 v5, s7
	s_add_i32 s18, s1, 0x4000
	v_and_b32_e32 v52, 24, v4
	v_ashrrev_i32_e32 v55, 31, v54
	v_add_u32_e32 v12, s4, v54
	v_ashrrev_i32_e32 v9, 31, v8
	v_or_b32_e32 v4, s6, v0
	v_mov_b64_e32 v[2:3], s[12:13]
	v_mov_b32_e32 v6, s20
	v_mov_b32_e32 v7, s21
	v_lshl_add_u64 v[10:11], s[18:19], 0, v[54:55]
	v_add_u32_e32 v12, 0x180, v12
	v_lshl_add_u64 v[56:57], v[4:5], 0, v[8:9]
	s_bfe_u32 s5, s40, 0x20004
	v_lshlrev_b32_e32 v36, 3, v32
	v_mad_u64_u32 v[4:5], s[20:21], v10, s2, v[2:3]
	v_mad_i64_i32 v[6:7], s[20:21], v12, s33, v[6:7]
	v_mad_u64_u32 v[2:3], s[20:21], v56, s2, v[2:3]
	s_lshl_b32 s14, s5, 7
	s_lshl_b32 s8, s4, 1
	v_and_b32_e32 v53, 56, v36
	v_mad_i32_i24 v5, v11, s2, v5
	s_mov_b64 s[20:21], 0x17700000
	v_mad_i32_i24 v3, v57, s2, v3
	v_lshlrev_b32_e32 v0, 1, v52
	v_lshlrev_b32_e32 v30, 1, v53
	v_lshl_add_u64 v[34:35], v[6:7], 0, s[20:21]
	v_lshl_add_u64 v[4:5], v[4:5], 0, s[8:9]
	v_lshl_add_u64 v[2:3], v[2:3], 0, s[14:15]
	v_lshl_add_u64 v[6:7], s[18:19], 1, v[34:35]
	v_lshl_add_u64 v[4:5], v[4:5], 0, v[30:31]
	v_lshl_add_u64 v[2:3], v[2:3], 0, v[0:1]
	v_lshl_add_u64 v[6:7], v[6:7], 0, v[30:31]
	global_load_dwordx4 v[22:25], v[4:5], off offset:2304
	global_load_dwordx4 v[26:29], v[6:7], off
	global_load_dwordx4 v[14:17], v[2:3], off offset:1792
	global_load_dwordx4 v[18:21], v[2:3], off offset:1856
	v_lshlrev_b32_e32 v37, 4, v32
	v_lshlrev_b32_e32 v32, 1, v32
	s_movk_i32 s9, 0x90
	v_cndmask_b32_e32 v6, v219, v222, vcc
	v_cmp_lt_i32_e32 vcc, v221, v220
	v_and_b32_e32 v36, 32, v36
	v_and_b32_e32 v37, 16, v37
	v_and_b32_e32 v32, 4, v32
	v_mul_lo_u32 v38, v54, s9
	v_cndmask_b32_e32 v7, v219, v221, vcc
	v_mov_b32_e32 v4, v1
	v_mov_b32_e32 v5, v1
	v_mul_u32_u24_e32 v65, 0x90, v33
	v_or3_b32 v66, v36, v37, v32
	v_add_u32_e32 v67, 16, v38
	v_lshl_add_u64 v[32:33], s[12:13], 0, v[30:31]
	s_or_b32 s18, s8, 0x900
	v_mov_b32_e32 v2, v1
	v_mov_b32_e32 v3, v1
	v_lshlrev_b32_e32 v63, 2, v6
	v_lshlrev_b32_e32 v62, 2, v7
	v_mov_b64_e32 v[8:9], v[4:5]
	v_mov_b64_e32 v[12:13], v[4:5]
	v_add_u32_e32 v36, v67, v30
	v_lshl_add_u64 v[58:59], v[34:35], 0, v[30:31]
	v_lshl_add_u64 v[60:61], v[32:33], 0, s[18:19]
	v_mov_b64_e32 v[32:33], v[4:5]
	s_mov_b32 s4, 0
	s_movk_i32 s14, 0x4040
	v_mov_b64_e32 v[6:7], v[2:3]
	v_mov_b64_e32 v[10:11], v[2:3]
	s_lshl_b32 s5, s5, 6
	v_lshl_add_u32 v37, v66, 1, v67
	v_mov_b64_e32 v[30:31], v[2:3]
	v_add_u32_e32 v37, 0x2000, v37
	s_waitcnt vmcnt(0) lgkmcnt(0)
	ds_write_b128 v36, v[22:25]
	ds_write2_b64 v37, v[26:27], v[28:29] offset0:128 offset1:130
	s_waitcnt lgkmcnt(0)
	s_barrier
	s_branch .LBB0_887

.LBB0_968:
	s_branch .LBB0_979
	v_mov_b32_e32 v2, s64
	v_mov_b32_e32 v3, s65
	v_mov_b32_e32 v4, s64
	v_readfirstlane_b32 s0, v2
	v_readfirstlane_b32 s1, v3
	v_mov_b32_e32 v5, s65
	v_mov_b32_e32 v2, s0
	v_mov_b32_e32 v3, s1
	global_load_dwordx2 v[2:3], v[2:3], off offset:248
	s_waitcnt vmcnt(0) lgkmcnt(0)
	v_mov_b32_e32 v0, s64
	v_readfirstlane_b32 s0, v4
	v_readfirstlane_b32 s1, v5
	v_mov_b32_e32 v6, s65
	v_mov_b32_e32 v4, s0
	v_mov_b32_e32 v5, s1
	global_load_dwordx2 v[4:5], v[4:5], off offset:248
	v_mov_b32_e32 v60, v247
	v_mov_b32_e32 v15, v1
	v_cmp_lt_i32_e32 vcc, v222, v220
	v_mov_b32_e32 v68, 0xf149f2ca
	v_mov_b32_e32 v62, 0
	s_waitcnt vmcnt(0) lgkmcnt(0)
	v_mov_b32_e32 v8, v5
	s_nop 0
	v_readfirstlane_b32 s0, v0
	v_readfirstlane_b32 s1, v6
	v_readfirstlane_b32 s13, v8
	v_mov_b32_e32 v6, s0
	v_readfirstlane_b32 s0, v2
	v_mov_b32_e32 v7, s1
	v_readfirstlane_b32 s1, v3
	s_add_u32 s8, s0, 0x9f00000
	global_load_dwordx2 v[50:51], v[6:7], off offset:248
	s_addc_u32 s9, s1, 0
	s_ashr_i32 s4, s40, 6
	s_lshl_b32 s0, s40, 7
	s_lshl_b32 s6, s40, 1
	s_ashr_i32 s5, s4, 31
	s_and_b32 s12, s0, 0x780
	s_waitcnt vmcnt(0) lgkmcnt(0)
	s_and_b32 s14, s6, 64
	v_ashrrev_i32_e32 v0, 2, v60
	v_and_b32_e32 v34, 15, v60
	s_lshl_b64 s[6:7], s[4:5], 11
	v_ashrrev_i32_e32 v52, 3, v60
	v_and_b32_e32 v8, -16, v0
	v_or_b32_e32 v0, s12, v34
	v_mov_b32_e32 v5, s7
	v_readfirstlane_b32 s5, v4
	v_add_u32_e32 v11, s14, v52
	v_ashrrev_i32_e32 v9, 31, v8
	v_or_b32_e32 v4, s6, v0
	v_mov_b64_e32 v[2:3], s[8:9]
	v_mov_b32_e32 v6, s5
	v_mov_b32_e32 v7, s13
	v_add_u32_e32 v0, 0x180, v11
	v_lshl_add_u64 v[54:55], v[4:5], 0, v[8:9]
	s_bfe_u32 s1, s40, 0x20004
	v_mad_i64_i32 v[4:5], s[12:13], v0, s33, v[6:7]
	v_mad_u64_u32 v[6:7], s[12:13], v54, s2, v[2:3]
	s_lshl_b32 s0, s1, 6
	s_lshl_b32 s18, s1, 7
	s_lshl_b32 s1, s4, 8
	s_mov_b64 s[12:13], 0x17700000
	v_mad_i32_i24 v7, v55, s2, v7
	s_ashr_i32 s4, s1, 31
	v_lshl_add_u64 v[16:17], v[4:5], 0, s[12:13]
	v_lshl_add_u64 v[4:5], v[6:7], 0, s[18:19]
	s_lshl_b32 s18, s14, 1
	s_add_u32 s12, s1, 0x4000
	v_ashrrev_i32_e32 v53, 31, v52
	s_addc_u32 s13, s4, 0
	v_lshl_add_u64 v[6:7], s[12:13], 0, v[52:53]
	v_lshlrev_b32_e32 v35, 3, v60
	v_lshl_add_u64 v[8:9], s[12:13], 1, v[16:17]
	v_mad_u64_u32 v[2:3], s[12:13], v6, s2, v[2:3]
	v_lshrrev_b32_e32 v10, 1, v60
	v_and_b32_e32 v61, 56, v35
	v_mad_i32_i24 v3, v7, s2, v3
	v_lshlrev_b32_e32 v14, 1, v61
	v_lshl_add_u64 v[2:3], v[2:3], 0, s[18:19]
	v_and_b32_e32 v0, 24, v10
	v_lshl_add_u64 v[2:3], v[2:3], 0, v[14:15]
	v_lshlrev_b32_e32 v0, 1, v0
	v_lshl_add_u64 v[8:9], v[8:9], 0, v[14:15]
	global_load_dwordx4 v[30:33], v[2:3], off offset:2304
	v_lshl_add_u64 v[2:3], v[4:5], 0, v[0:1]
	global_load_dwordx4 v[26:29], v[8:9], off
	global_load_dwordx4 v[18:21], v[2:3], off offset:1792
	global_load_dwordx4 v[22:25], v[2:3], off offset:1856
	v_lshlrev_b32_e32 v36, 4, v60
	v_lshlrev_b32_e32 v37, 1, v60
	s_movk_i32 s13, 0x90
	v_cndmask_b32_e32 v6, v219, v222, vcc
	v_cmp_lt_i32_e32 vcc, v221, v220
	v_and_b32_e32 v35, 32, v35
	v_and_b32_e32 v36, 16, v36
	v_and_b32_e32 v37, 4, v37
	v_mul_lo_u32 v38, v52, s13
	v_cndmask_b32_e32 v7, v219, v221, vcc
	v_mov_b32_e32 v4, v1
	v_mov_b32_e32 v5, v1
	v_or3_b32 v66, v35, v36, v37
	v_add_u32_e32 v67, 16, v38
	v_mov_b32_e32 v2, v1
	v_mov_b32_e32 v3, v1
	v_lshlrev_b32_e32 v64, 2, v6
	v_lshlrev_b32_e32 v63, 2, v7
	v_mov_b64_e32 v[8:9], v[4:5]
	v_mov_b64_e32 v[12:13], v[4:5]
	v_mul_u32_u24_e32 v65, 0x90, v34
	v_add_u32_e32 v36, v67, v14
	v_lshl_add_u32 v37, v66, 1, v67
	v_lshl_add_u64 v[34:35], s[8:9], 0, v[14:15]
	v_lshl_add_u64 v[56:57], v[16:17], 0, v[14:15]
	s_or_b32 s18, s18, 0x900
	v_mov_b64_e32 v[16:17], v[4:5]
	s_mov_b32 s5, 0
	s_movk_i32 s12, 0x4040
	v_mov_b64_e32 v[6:7], v[2:3]
	v_mov_b64_e32 v[10:11], v[2:3]
	v_add_u32_e32 v37, 0x2000, v37
	v_lshl_add_u64 v[58:59], v[34:35], 0, s[18:19]
	v_mov_b64_e32 v[14:15], v[2:3]
	s_waitcnt vmcnt(0) lgkmcnt(0)
	ds_write2_b64 v37, v[26:27], v[28:29] offset0:128 offset1:130
	ds_write_b128 v36, v[30:33]
	s_waitcnt lgkmcnt(0)
	s_barrier
	s_branch .LBB0_970

.Lga_entry:
	s_mov_b64 exec, -1
	s_load_dwordx2 s[4:5], s[64:65], 0xf8
	s_mov_b32 s100, 0x3e38aa3b
	v_mov_b32_e32 v86, 0x3e38aa3b
	v_and_b32_e32 v144, 63, v247
	v_lshrrev_b32_e32 v145, 6, v247
	v_and_b32_e32 v146, 15, v144
	v_lshrrev_b32_e32 v147, 4, v144
	v_readfirstlane_b32 s21, v145
	v_bfe_u32 v148, v146, 1, 3
	v_lshlrev_b32_e32 v149, 7, v146
	v_xor_b32_e32 v150, v147, v148
	v_lshl_add_u32 v136, v150, 4, v149
	v_add_u32_e32 v136, 16, v136
	v_xor_b32_e32 v150, 4, v150
	v_lshl_add_u32 v137, v150, 4, v149
	v_add_u32_e32 v137, 16, v137
	v_lshrrev_b32_e32 v151, 1, v147
	v_and_b32_e32 v152, 1, v147
	v_lshlrev_b32_e32 v152, 3, v152
	v_add_u32_e32 v152, v152, v149
	v_add_u32_e32 v152, 0x2010, v152
	v_add_u32_e32 v153, 0, v151
	v_xor_b32_e32 v153, v153, v148
	v_lshl_add_u32 v138, v153, 4, v152
	v_add_u32_e32 v153, 2, v151
	v_xor_b32_e32 v153, v153, v148
	v_lshl_add_u32 v139, v153, 4, v152
	v_add_u32_e32 v153, 4, v151
	v_xor_b32_e32 v153, v153, v148
	v_lshl_add_u32 v140, v153, 4, v152
	v_add_u32_e32 v153, 6, v151
	v_xor_b32_e32 v153, v153, v148
	v_lshl_add_u32 v141, v153, 4, v152
	s_lshl_b32 s0, s21, 3
	v_lshrrev_b32_e32 v153, 3, v144
	v_add_u32_e32 v153, s0, v153
	v_bfe_u32 v154, v153, 1, 3
	v_and_b32_e32 v155, 7, v144
	v_xor_b32_e32 v154, v154, v155
	v_lshlrev_b32_e32 v154, 4, v154
	v_mul_u32_u24_e32 v142, 0x3000, v153
	v_add_u32_e32 v142, v142, v154
	v_mul_u32_u24_e32 v143, 0x9000, v153
	v_add_u32_e32 v143, v143, v154
	s_lshl_b32 s32, s21, 10
	s_add_u32 s32, s32, 16
	s_add_u32 s41, s32, 0x2000
	s_sub_u32 s1, s40, 144
	s_waitcnt lgkmcnt(0)
.Lga_unit:
	v_and_b32_e32 v144, 63, v247
	s_and_b32 s80, s1, 15
	s_bfe_u32 s81, s1, 0x10004
	s_lshr_b32 s43, s1, 5
	s_lshl_b32 s0, s81, 7
	s_add_u32 s0, s0, 0x900
	s_add_u32 s6, s4, 0x9f00000
	s_addc_u32 s7, s5, 0
	s_add_u32 s6, s6, s0
	s_addc_u32 s7, s7, 0
	s_mul_i32 s0, s43, 0x1800000
	s_add_u32 s96, s6, s0
	s_addc_u32 s97, s7, 0
	s_mul_i32 s0, s43, 0x300000
	s_add_u32 s6, s6, s0
	s_addc_u32 s7, s7, 0
	s_add_u32 s6, s6, 0xc000000
	s_addc_u32 s7, s7, 0
	s_lshl_b32 s0, s81, 6
	s_add_u32 s0, s0, 0x180
	s_mul_i32 s0, s0, 0x9000
	s_add_u32 s8, s4, 0x17700000
	s_addc_u32 s9, s5, 0
	s_add_u32 s8, s8, s0
	s_addc_u32 s9, s9, 0
	s_lshl_b32 s0, s43, 12
	s_add_u32 s98, s8, s0
	s_addc_u32 s99, s9, 0
	s_lshl_b32 s0, s43, 9
	s_add_u32 s0, s0, 0x8000
	s_add_u32 s8, s8, s0
	s_addc_u32 s9, s9, 0
	s_lshl_b32 s0, s43, 11
	s_lshl_b32 s92, s80, 7
	s_add_u32 s0, s0, s92
	s_lshl_b32 s92, s21, 4
	s_add_u32 s0, s0, s92
	v_and_b32_e32 v146, 15, v144
	v_add_u32_e32 v146, s0, v146
	v_lshrrev_b32_e32 v147, 4, v144
	s_lshl_b32 s92, s81, 8
	s_add_u32 s92, s92, 0x700
	v_lshl_add_u32 v148, v147, 4, s92
	v_mov_b32_e32 v149, 0
	s_movk_i32 s93, 0x3000
	v_mad_u64_u32 v[82:83], s[90:91], v146, s93, v[148:149]
	s_add_u32 s90, s4, 0x9f00000
	s_addc_u32 s91, s5, 0
	v_lshl_add_u64 v[82:83], v[82:83], 0, s[90:91]
	global_load_dwordx4 v[2:5], v[82:83], off
	global_load_dwordx4 v[6:9], v[82:83], off offset:64
	global_load_dwordx4 v[10:13], v[82:83], off offset:128
	global_load_dwordx4 v[14:17], v[82:83], off offset:192
	s_lshl_b32 s92, s81, 8
	s_add_u32 s92, s92, 0x400
	v_lshl_add_u32 v148, v147, 3, s92
	v_lshlrev_b32_e32 v150, 11, v146
	v_add_u32_e32 v148, v148, v150
	s_add_u32 s90, s4, 0x1e300000
	s_addc_u32 s91, s5, 0
	v_lshl_add_u64 v[84:85], s[90:91], 0, v[148:149]
	v_mov_b32_e32 v100, 0
	v_mov_b32_e32 v101, 0
	v_mov_b32_e32 v102, 0
	v_mov_b32_e32 v103, 0
	v_mov_b32_e32 v104, 0
	v_mov_b32_e32 v105, 0
	v_mov_b32_e32 v106, 0
	v_mov_b32_e32 v107, 0
	v_mov_b32_e32 v108, 0
	v_mov_b32_e32 v109, 0
	v_mov_b32_e32 v110, 0
	v_mov_b32_e32 v111, 0
	v_mov_b32_e32 v112, 0
	v_mov_b32_e32 v113, 0
	v_mov_b32_e32 v114, 0
	v_mov_b32_e32 v115, 0
	v_mov_b32_e32 v116, 0
	v_mov_b32_e32 v117, 0
	v_mov_b32_e32 v118, 0
	v_mov_b32_e32 v119, 0
	v_mov_b32_e32 v120, 0
	v_mov_b32_e32 v121, 0
	v_mov_b32_e32 v122, 0
	v_mov_b32_e32 v123, 0
	v_mov_b32_e32 v124, 0
	v_mov_b32_e32 v125, 0
	v_mov_b32_e32 v126, 0
	v_mov_b32_e32 v127, 0
	v_mov_b32_e32 v128, 0
	v_mov_b32_e32 v129, 0
	v_mov_b32_e32 v130, 0
	v_mov_b32_e32 v131, 0
	v_mov_b32_e32 v132, 0xf149f2ca
	v_mov_b32_e32 v133, 0xf149f2ca
	v_mov_b32_e32 v134, 0
	v_mov_b32_e32 v135, 0
	s_mov_b32 s89, 0
	s_mov_b32 s42, 36
	s_cmp_eq_u32 s89, 4
	s_cbranch_scc0 .Lga_nosw1
	s_mov_b64 s[6:7], s[96:97]
	s_mov_b64 s[8:9], s[98:99]
.Lga_nosw1:
	s_add_i32 m0, s32, 0
	s_nop 0
	global_load_lds_dwordx4 v142, s[6:7]
	s_add_i32 m0, s41, 0
	s_nop 0
	global_load_lds_dwordx4 v143, s[8:9]
	s_add_u32 s6, s6, 0xc0000
	s_addc_u32 s7, s7, 0
	s_add_u32 s8, s8, 0x80
	s_addc_u32 s9, s9, 0
	s_add_u32 s89, s89, 1
	s_cmp_eq_u32 s89, 4
	s_cbranch_scc0 .Lga_nosw2
	s_mov_b64 s[6:7], s[96:97]
	s_mov_b64 s[8:9], s[98:99]
.Lga_nosw2:
	s_add_i32 m0, s32, 16384
	s_nop 0
	global_load_lds_dwordx4 v142, s[6:7]
	s_add_i32 m0, s41, 16384
	s_nop 0
	global_load_lds_dwordx4 v143, s[8:9]
	s_add_u32 s6, s6, 0xc0000
	s_addc_u32 s7, s7, 0
	s_add_u32 s8, s8, 0x80
	s_addc_u32 s9, s9, 0
	s_add_u32 s89, s89, 1
	s_cmp_eq_u32 s89, 4
	s_cbranch_scc0 .Lga_nosw3
	s_mov_b64 s[6:7], s[96:97]
	s_mov_b64 s[8:9], s[98:99]
.Lga_nosw3:
	s_add_i32 m0, s32, 32768
	s_nop 0
	global_load_lds_dwordx4 v142, s[6:7]
	s_add_i32 m0, s41, 32768
	s_nop 0
	global_load_lds_dwordx4 v143, s[8:9]
	s_add_u32 s6, s6, 0xc0000
	s_addc_u32 s7, s7, 0
	s_add_u32 s8, s8, 0x80
	s_addc_u32 s9, s9, 0
	s_add_u32 s89, s89, 1
.Lga_loop:
	s_cmp_lt_u32 s42, 3
	s_cbranch_scc1 .Lga_tail0
	s_waitcnt vmcnt(4)
	s_barrier
	s_cmp_lt_u32 s42, 4
	s_cbranch_scc1 .Lga_go0
	s_cmp_eq_u32 s89, 4
	s_cbranch_scc0 .Lga_nosw4
	s_mov_b64 s[6:7], s[96:97]
	s_mov_b64 s[8:9], s[98:99]
.Lga_nosw4:
	s_add_i32 m0, s32, 49152
	s_nop 0
	global_load_lds_dwordx4 v142, s[6:7]
	s_add_i32 m0, s41, 49152
	s_nop 0
	global_load_lds_dwordx4 v143, s[8:9]
	s_add_u32 s6, s6, 0xc0000
	s_addc_u32 s7, s7, 0
	s_add_u32 s8, s8, 0x80
	s_addc_u32 s9, s9, 0
	s_add_u32 s89, s89, 1
	s_branch .Lga_go0

.Lga_go0:
	ds_read_b128 v[18:21], v136 offset:0
	ds_read_b128 v[22:25], v137 offset:0
	ds_read_b128 v[26:29], v136 offset:2048
	ds_read_b128 v[30:33], v137 offset:2048
	ds_read_b128 v[34:37], v136 offset:4096
	ds_read_b128 v[38:41], v137 offset:4096
	ds_read_b128 v[42:45], v136 offset:6144
	ds_read_b128 v[46:49], v137 offset:6144
	s_waitcnt lgkmcnt(0)
	v_mfma_f32_16x16x32_bf16 v[50:53], v[18:21], v[2:5], 0
	v_mfma_f32_16x16x32_bf16 v[54:57], v[26:29], v[2:5], 0
	v_mfma_f32_16x16x32_bf16 v[58:61], v[34:37], v[2:5], 0
	v_mfma_f32_16x16x32_bf16 v[62:65], v[42:45], v[2:5], 0
	v_mfma_f32_16x16x32_bf16 v[50:53], v[22:25], v[6:9], v[50:53]
	v_mfma_f32_16x16x32_bf16 v[54:57], v[30:33], v[6:9], v[54:57]
	v_mfma_f32_16x16x32_bf16 v[58:61], v[38:41], v[6:9], v[58:61]
	v_mfma_f32_16x16x32_bf16 v[62:65], v[46:49], v[6:9], v[62:65]
	ds_read_b64 v[168:169], v138 offset:0
	ds_read_b64 v[170:171], v139 offset:0
	ds_read_b64 v[172:173], v140 offset:0
	ds_read_b64 v[174:175], v141 offset:0
	ds_read_b64 v[176:177], v138 offset:2048
	ds_read_b64 v[178:179], v139 offset:2048
	ds_read_b64 v[180:181], v140 offset:2048
	ds_read_b64 v[182:183], v141 offset:2048
	v_mfma_f32_16x16x32_bf16 v[66:69], v[18:21], v[10:13], 0
	v_mfma_f32_16x16x32_bf16 v[70:73], v[26:29], v[10:13], 0
	v_mfma_f32_16x16x32_bf16 v[74:77], v[34:37], v[10:13], 0
	v_mfma_f32_16x16x32_bf16 v[78:81], v[42:45], v[10:13], 0
	v_mfma_f32_16x16x32_bf16 v[66:69], v[22:25], v[14:17], v[66:69]
	v_mfma_f32_16x16x32_bf16 v[70:73], v[30:33], v[14:17], v[70:73]
	v_mfma_f32_16x16x32_bf16 v[74:77], v[38:41], v[14:17], v[74:77]
	v_mfma_f32_16x16x32_bf16 v[78:81], v[46:49], v[14:17], v[78:81]
	ds_read_b64 v[184:185], v138 offset:4096
	ds_read_b64 v[186:187], v139 offset:4096
	ds_read_b64 v[188:189], v140 offset:4096
	ds_read_b64 v[190:191], v141 offset:4096
	ds_read_b64 v[192:193], v138 offset:6144
	ds_read_b64 v[194:195], v139 offset:6144
	ds_read_b64 v[196:197], v140 offset:6144
	ds_read_b64 v[198:199], v141 offset:6144
	s_nop 3
	v_max3_f32 v144, v50, v51, v52
	v_max3_f32 v145, v53, v54, v55
	v_max3_f32 v150, v56, v57, v58
	v_max3_f32 v151, v59, v60, v61
	v_max3_f32 v152, v62, v63, v64
	v_max3_f32 v144, v144, v145, v65
	v_max3_f32 v144, v144, v150, v151
	v_max_f32_e32 v144, v144, v152
	v_mov_b32_e32 v145, v144
	s_nop 1
	v_permlane16_swap_b32_e32 v144, v145
	v_max_f32_e32 v144, v144, v145
	v_mov_b32_e32 v145, v144
	s_nop 1
	v_permlane32_swap_b32_e32 v144, v145
	v_max_f32_e32 v144, v144, v145
	v_mul_f32_e32 v144, s100, v144
	v_max_f32_e32 v146, v132, v144
	v_cmp_gt_f32_e32 vcc, v146, v132
	s_cbranch_vccz .Lga_nors1
	v_sub_f32_e32 v148, v132, v146
	v_exp_f32_e32 v148, v148
	v_mov_b32_e32 v132, v146
	s_nop 0
	v_mul_f32_e32 v134, v134, v148
	v_pk_mul_f32 v[100:101], v[100:101], v[148:149] op_sel_hi:[1,0]
	v_pk_mul_f32 v[102:103], v[102:103], v[148:149] op_sel_hi:[1,0]
	v_pk_mul_f32 v[104:105], v[104:105], v[148:149] op_sel_hi:[1,0]
	v_pk_mul_f32 v[106:107], v[106:107], v[148:149] op_sel_hi:[1,0]
	v_pk_mul_f32 v[108:109], v[108:109], v[148:149] op_sel_hi:[1,0]
	v_pk_mul_f32 v[110:111], v[110:111], v[148:149] op_sel_hi:[1,0]
	v_pk_mul_f32 v[112:113], v[112:113], v[148:149] op_sel_hi:[1,0]
	v_pk_mul_f32 v[114:115], v[114:115], v[148:149] op_sel_hi:[1,0]
.Lga_nors1:
	v_pk_fma_f32 v[50:51], v[50:51], v[86:87], v[146:147] op_sel_hi:[1,0,0] neg_lo:[0,0,1] neg_hi:[0,0,1]
	v_pk_fma_f32 v[52:53], v[52:53], v[86:87], v[146:147] op_sel_hi:[1,0,0] neg_lo:[0,0,1] neg_hi:[0,0,1]
	v_pk_fma_f32 v[54:55], v[54:55], v[86:87], v[146:147] op_sel_hi:[1,0,0] neg_lo:[0,0,1] neg_hi:[0,0,1]
	v_pk_fma_f32 v[56:57], v[56:57], v[86:87], v[146:147] op_sel_hi:[1,0,0] neg_lo:[0,0,1] neg_hi:[0,0,1]
	v_pk_fma_f32 v[58:59], v[58:59], v[86:87], v[146:147] op_sel_hi:[1,0,0] neg_lo:[0,0,1] neg_hi:[0,0,1]
	v_pk_fma_f32 v[60:61], v[60:61], v[86:87], v[146:147] op_sel_hi:[1,0,0] neg_lo:[0,0,1] neg_hi:[0,0,1]
	v_pk_fma_f32 v[62:63], v[62:63], v[86:87], v[146:147] op_sel_hi:[1,0,0] neg_lo:[0,0,1] neg_hi:[0,0,1]
	v_pk_fma_f32 v[64:65], v[64:65], v[86:87], v[146:147] op_sel_hi:[1,0,0] neg_lo:[0,0,1] neg_hi:[0,0,1]
	v_exp_f32_e32 v50, v50
	v_exp_f32_e32 v51, v51
	v_exp_f32_e32 v52, v52
	v_exp_f32_e32 v53, v53
	v_exp_f32_e32 v54, v54
	v_exp_f32_e32 v55, v55
	v_exp_f32_e32 v56, v56
	v_exp_f32_e32 v57, v57
	v_exp_f32_e32 v58, v58
	v_exp_f32_e32 v59, v59
	v_exp_f32_e32 v60, v60
	v_exp_f32_e32 v61, v61
	v_exp_f32_e32 v62, v62
	v_exp_f32_e32 v63, v63
	v_exp_f32_e32 v64, v64
	v_exp_f32_e32 v65, v65
	v_pk_add_f32 v[150:151], v[50:51], v[52:53]
	v_pk_add_f32 v[152:153], v[54:55], v[56:57]
	v_pk_add_f32 v[154:155], v[58:59], v[60:61]
	v_pk_add_f32 v[156:157], v[62:63], v[64:65]
	v_pk_add_f32 v[150:151], v[150:151], v[152:153]
	v_pk_add_f32 v[154:155], v[154:155], v[156:157]
	v_pk_add_f32 v[150:151], v[150:151], v[154:155]
	v_add_f32_e32 v150, v150, v151
	v_add_f32_e32 v134, v134, v150
	v_cvt_pk_bf16_f32 v200, v50, v51
	v_cvt_pk_bf16_f32 v201, v52, v53
	v_cvt_pk_bf16_f32 v202, v54, v55
	v_cvt_pk_bf16_f32 v203, v56, v57
	v_cvt_pk_bf16_f32 v204, v58, v59
	v_cvt_pk_bf16_f32 v205, v60, v61
	v_cvt_pk_bf16_f32 v206, v62, v63
	v_cvt_pk_bf16_f32 v207, v64, v65
	s_waitcnt lgkmcnt(0)
	s_nop 1
	v_mfma_f32_16x16x32_bf16 v[100:103], v[168:171], v[200:203], v[100:103]
	v_mfma_f32_16x16x32_bf16 v[100:103], v[172:175], v[204:207], v[100:103]
	v_mfma_f32_16x16x32_bf16 v[104:107], v[176:179], v[200:203], v[104:107]
	v_mfma_f32_16x16x32_bf16 v[104:107], v[180:183], v[204:207], v[104:107]
	v_mfma_f32_16x16x32_bf16 v[108:111], v[184:187], v[200:203], v[108:111]
	v_mfma_f32_16x16x32_bf16 v[108:111], v[188:191], v[204:207], v[108:111]
	v_mfma_f32_16x16x32_bf16 v[112:115], v[192:195], v[200:203], v[112:115]
	v_mfma_f32_16x16x32_bf16 v[112:115], v[196:199], v[204:207], v[112:115]
	v_max3_f32 v144, v66, v67, v68
	v_max3_f32 v145, v69, v70, v71
	v_max3_f32 v150, v72, v73, v74
	v_max3_f32 v151, v75, v76, v77
	v_max3_f32 v152, v78, v79, v80
	v_max3_f32 v144, v144, v145, v81
	v_max3_f32 v144, v144, v150, v151
	v_max_f32_e32 v144, v144, v152
	v_mov_b32_e32 v145, v144
	s_nop 1
	v_permlane16_swap_b32_e32 v144, v145
	v_max_f32_e32 v144, v144, v145
	v_mov_b32_e32 v145, v144
	s_nop 1
	v_permlane32_swap_b32_e32 v144, v145
	v_max_f32_e32 v144, v144, v145
	v_mul_f32_e32 v144, s100, v144
	v_max_f32_e32 v146, v133, v144
	v_cmp_gt_f32_e32 vcc, v146, v133
	s_cbranch_vccz .Lga_nors2
	v_sub_f32_e32 v148, v133, v146
	v_exp_f32_e32 v148, v148
	v_mov_b32_e32 v133, v146
	s_nop 0
	v_mul_f32_e32 v135, v135, v148
	v_pk_mul_f32 v[116:117], v[116:117], v[148:149] op_sel_hi:[1,0]
	v_pk_mul_f32 v[118:119], v[118:119], v[148:149] op_sel_hi:[1,0]
	v_pk_mul_f32 v[120:121], v[120:121], v[148:149] op_sel_hi:[1,0]
	v_pk_mul_f32 v[122:123], v[122:123], v[148:149] op_sel_hi:[1,0]
	v_pk_mul_f32 v[124:125], v[124:125], v[148:149] op_sel_hi:[1,0]
	v_pk_mul_f32 v[126:127], v[126:127], v[148:149] op_sel_hi:[1,0]
	v_pk_mul_f32 v[128:129], v[128:129], v[148:149] op_sel_hi:[1,0]
	v_pk_mul_f32 v[130:131], v[130:131], v[148:149] op_sel_hi:[1,0]
.Lga_nors2:
	v_pk_fma_f32 v[66:67], v[66:67], v[86:87], v[146:147] op_sel_hi:[1,0,0] neg_lo:[0,0,1] neg_hi:[0,0,1]
	v_pk_fma_f32 v[68:69], v[68:69], v[86:87], v[146:147] op_sel_hi:[1,0,0] neg_lo:[0,0,1] neg_hi:[0,0,1]
	v_pk_fma_f32 v[70:71], v[70:71], v[86:87], v[146:147] op_sel_hi:[1,0,0] neg_lo:[0,0,1] neg_hi:[0,0,1]
	v_pk_fma_f32 v[72:73], v[72:73], v[86:87], v[146:147] op_sel_hi:[1,0,0] neg_lo:[0,0,1] neg_hi:[0,0,1]
	v_pk_fma_f32 v[74:75], v[74:75], v[86:87], v[146:147] op_sel_hi:[1,0,0] neg_lo:[0,0,1] neg_hi:[0,0,1]
	v_pk_fma_f32 v[76:77], v[76:77], v[86:87], v[146:147] op_sel_hi:[1,0,0] neg_lo:[0,0,1] neg_hi:[0,0,1]
	v_pk_fma_f32 v[78:79], v[78:79], v[86:87], v[146:147] op_sel_hi:[1,0,0] neg_lo:[0,0,1] neg_hi:[0,0,1]
	v_pk_fma_f32 v[80:81], v[80:81], v[86:87], v[146:147] op_sel_hi:[1,0,0] neg_lo:[0,0,1] neg_hi:[0,0,1]
	v_exp_f32_e32 v66, v66
	v_exp_f32_e32 v67, v67
	v_exp_f32_e32 v68, v68
	v_exp_f32_e32 v69, v69
	v_exp_f32_e32 v70, v70
	v_exp_f32_e32 v71, v71
	v_exp_f32_e32 v72, v72
	v_exp_f32_e32 v73, v73
	v_exp_f32_e32 v74, v74
	v_exp_f32_e32 v75, v75
	v_exp_f32_e32 v76, v76
	v_exp_f32_e32 v77, v77
	v_exp_f32_e32 v78, v78
	v_exp_f32_e32 v79, v79
	v_exp_f32_e32 v80, v80
	v_exp_f32_e32 v81, v81
	v_pk_add_f32 v[150:151], v[66:67], v[68:69]
	v_pk_add_f32 v[152:153], v[70:71], v[72:73]
	v_pk_add_f32 v[154:155], v[74:75], v[76:77]
	v_pk_add_f32 v[156:157], v[78:79], v[80:81]
	v_pk_add_f32 v[150:151], v[150:151], v[152:153]
	v_pk_add_f32 v[154:155], v[154:155], v[156:157]
	v_pk_add_f32 v[150:151], v[150:151], v[154:155]
	v_add_f32_e32 v150, v150, v151
	v_add_f32_e32 v135, v135, v150
	v_cvt_pk_bf16_f32 v208, v66, v67
	v_cvt_pk_bf16_f32 v209, v68, v69
	v_cvt_pk_bf16_f32 v210, v70, v71
	v_cvt_pk_bf16_f32 v211, v72, v73
	v_cvt_pk_bf16_f32 v212, v74, v75
	v_cvt_pk_bf16_f32 v213, v76, v77
	v_cvt_pk_bf16_f32 v214, v78, v79
	v_cvt_pk_bf16_f32 v215, v80, v81
	s_nop 1
	v_mfma_f32_16x16x32_bf16 v[116:119], v[168:171], v[208:211], v[116:119]
	v_mfma_f32_16x16x32_bf16 v[116:119], v[172:175], v[212:215], v[116:119]
	v_mfma_f32_16x16x32_bf16 v[120:123], v[176:179], v[208:211], v[120:123]
	v_mfma_f32_16x16x32_bf16 v[120:123], v[180:183], v[212:215], v[120:123]
	v_mfma_f32_16x16x32_bf16 v[124:127], v[184:187], v[208:211], v[124:127]
	v_mfma_f32_16x16x32_bf16 v[124:127], v[188:191], v[212:215], v[124:127]
	v_mfma_f32_16x16x32_bf16 v[128:131], v[192:195], v[208:211], v[128:131]
	v_mfma_f32_16x16x32_bf16 v[128:131], v[196:199], v[212:215], v[128:131]
	s_sub_u32 s42, s42, 1
	s_cmp_lt_u32 s42, 3
	s_cbranch_scc1 .Lga_tail1
	s_waitcnt vmcnt(4)
	s_barrier
	s_cmp_lt_u32 s42, 4
	s_cbranch_scc1 .Lga_go1
	s_cmp_eq_u32 s89, 4
	s_cbranch_scc0 .Lga_nosw5
	s_mov_b64 s[6:7], s[96:97]
	s_mov_b64 s[8:9], s[98:99]
.Lga_nosw5:
	s_add_i32 m0, s32, 0
	s_nop 0
	global_load_lds_dwordx4 v142, s[6:7]
	s_add_i32 m0, s41, 0
	s_nop 0
	global_load_lds_dwordx4 v143, s[8:9]
	s_add_u32 s6, s6, 0xc0000
	s_addc_u32 s7, s7, 0
	s_add_u32 s8, s8, 0x80
	s_addc_u32 s9, s9, 0
	s_add_u32 s89, s89, 1
	s_branch .Lga_go1

.Lga_go1:
	ds_read_b128 v[18:21], v136 offset:16384
	ds_read_b128 v[22:25], v137 offset:16384
	ds_read_b128 v[26:29], v136 offset:18432
	ds_read_b128 v[30:33], v137 offset:18432
	ds_read_b128 v[34:37], v136 offset:20480
	ds_read_b128 v[38:41], v137 offset:20480
	ds_read_b128 v[42:45], v136 offset:22528
	ds_read_b128 v[46:49], v137 offset:22528
	s_waitcnt lgkmcnt(0)
	v_mfma_f32_16x16x32_bf16 v[50:53], v[18:21], v[2:5], 0
	v_mfma_f32_16x16x32_bf16 v[54:57], v[26:29], v[2:5], 0
	v_mfma_f32_16x16x32_bf16 v[58:61], v[34:37], v[2:5], 0
	v_mfma_f32_16x16x32_bf16 v[62:65], v[42:45], v[2:5], 0
	v_mfma_f32_16x16x32_bf16 v[50:53], v[22:25], v[6:9], v[50:53]
	v_mfma_f32_16x16x32_bf16 v[54:57], v[30:33], v[6:9], v[54:57]
	v_mfma_f32_16x16x32_bf16 v[58:61], v[38:41], v[6:9], v[58:61]
	v_mfma_f32_16x16x32_bf16 v[62:65], v[46:49], v[6:9], v[62:65]
	ds_read_b64 v[168:169], v138 offset:16384
	ds_read_b64 v[170:171], v139 offset:16384
	ds_read_b64 v[172:173], v140 offset:16384
	ds_read_b64 v[174:175], v141 offset:16384
	ds_read_b64 v[176:177], v138 offset:18432
	ds_read_b64 v[178:179], v139 offset:18432
	ds_read_b64 v[180:181], v140 offset:18432
	ds_read_b64 v[182:183], v141 offset:18432
	v_mfma_f32_16x16x32_bf16 v[66:69], v[18:21], v[10:13], 0
	v_mfma_f32_16x16x32_bf16 v[70:73], v[26:29], v[10:13], 0
	v_mfma_f32_16x16x32_bf16 v[74:77], v[34:37], v[10:13], 0
	v_mfma_f32_16x16x32_bf16 v[78:81], v[42:45], v[10:13], 0
	v_mfma_f32_16x16x32_bf16 v[66:69], v[22:25], v[14:17], v[66:69]
	v_mfma_f32_16x16x32_bf16 v[70:73], v[30:33], v[14:17], v[70:73]
	v_mfma_f32_16x16x32_bf16 v[74:77], v[38:41], v[14:17], v[74:77]
	v_mfma_f32_16x16x32_bf16 v[78:81], v[46:49], v[14:17], v[78:81]
	ds_read_b64 v[184:185], v138 offset:20480
	ds_read_b64 v[186:187], v139 offset:20480
	ds_read_b64 v[188:189], v140 offset:20480
	ds_read_b64 v[190:191], v141 offset:20480
	ds_read_b64 v[192:193], v138 offset:22528
	ds_read_b64 v[194:195], v139 offset:22528
	ds_read_b64 v[196:197], v140 offset:22528
	ds_read_b64 v[198:199], v141 offset:22528
	s_nop 3
	v_max3_f32 v144, v50, v51, v52
	v_max3_f32 v145, v53, v54, v55
	v_max3_f32 v150, v56, v57, v58
	v_max3_f32 v151, v59, v60, v61
	v_max3_f32 v152, v62, v63, v64
	v_max3_f32 v144, v144, v145, v65
	v_max3_f32 v144, v144, v150, v151
	v_max_f32_e32 v144, v144, v152
	v_mov_b32_e32 v145, v144
	s_nop 1
	v_permlane16_swap_b32_e32 v144, v145
	v_max_f32_e32 v144, v144, v145
	v_mov_b32_e32 v145, v144
	s_nop 1
	v_permlane32_swap_b32_e32 v144, v145
	v_max_f32_e32 v144, v144, v145
	v_mul_f32_e32 v144, s100, v144
	v_max_f32_e32 v146, v132, v144
	v_cmp_gt_f32_e32 vcc, v146, v132
	s_cbranch_vccz .Lga_nors3
	v_sub_f32_e32 v148, v132, v146
	v_exp_f32_e32 v148, v148
	v_mov_b32_e32 v132, v146
	s_nop 0
	v_mul_f32_e32 v134, v134, v148
	v_pk_mul_f32 v[100:101], v[100:101], v[148:149] op_sel_hi:[1,0]
	v_pk_mul_f32 v[102:103], v[102:103], v[148:149] op_sel_hi:[1,0]
	v_pk_mul_f32 v[104:105], v[104:105], v[148:149] op_sel_hi:[1,0]
	v_pk_mul_f32 v[106:107], v[106:107], v[148:149] op_sel_hi:[1,0]
	v_pk_mul_f32 v[108:109], v[108:109], v[148:149] op_sel_hi:[1,0]
	v_pk_mul_f32 v[110:111], v[110:111], v[148:149] op_sel_hi:[1,0]
	v_pk_mul_f32 v[112:113], v[112:113], v[148:149] op_sel_hi:[1,0]
	v_pk_mul_f32 v[114:115], v[114:115], v[148:149] op_sel_hi:[1,0]

.Lga_nosw6:
	s_add_i32 m0, s32, 16384
	s_nop 0
	global_load_lds_dwordx4 v142, s[6:7]
	s_add_i32 m0, s41, 16384
	s_nop 0
	global_load_lds_dwordx4 v143, s[8:9]
	s_add_u32 s6, s6, 0xc0000
	s_addc_u32 s7, s7, 0
	s_add_u32 s8, s8, 0x80
	s_addc_u32 s9, s9, 0
	s_add_u32 s89, s89, 1
	s_branch .Lga_go2

.Lga_go2:
	ds_read_b128 v[18:21], v136 offset:32768
	ds_read_b128 v[22:25], v137 offset:32768
	ds_read_b128 v[26:29], v136 offset:34816
	ds_read_b128 v[30:33], v137 offset:34816
	ds_read_b128 v[34:37], v136 offset:36864
	ds_read_b128 v[38:41], v137 offset:36864
	ds_read_b128 v[42:45], v136 offset:38912
	ds_read_b128 v[46:49], v137 offset:38912
	s_waitcnt lgkmcnt(0)
	v_mfma_f32_16x16x32_bf16 v[50:53], v[18:21], v[2:5], 0
	v_mfma_f32_16x16x32_bf16 v[54:57], v[26:29], v[2:5], 0
	v_mfma_f32_16x16x32_bf16 v[58:61], v[34:37], v[2:5], 0
	v_mfma_f32_16x16x32_bf16 v[62:65], v[42:45], v[2:5], 0
	v_mfma_f32_16x16x32_bf16 v[50:53], v[22:25], v[6:9], v[50:53]
	v_mfma_f32_16x16x32_bf16 v[54:57], v[30:33], v[6:9], v[54:57]
	v_mfma_f32_16x16x32_bf16 v[58:61], v[38:41], v[6:9], v[58:61]
	v_mfma_f32_16x16x32_bf16 v[62:65], v[46:49], v[6:9], v[62:65]
	ds_read_b64 v[168:169], v138 offset:32768
	ds_read_b64 v[170:171], v139 offset:32768
	ds_read_b64 v[172:173], v140 offset:32768
	ds_read_b64 v[174:175], v141 offset:32768
	ds_read_b64 v[176:177], v138 offset:34816
	ds_read_b64 v[178:179], v139 offset:34816
	ds_read_b64 v[180:181], v140 offset:34816
	ds_read_b64 v[182:183], v141 offset:34816
	v_mfma_f32_16x16x32_bf16 v[66:69], v[18:21], v[10:13], 0
	v_mfma_f32_16x16x32_bf16 v[70:73], v[26:29], v[10:13], 0
	v_mfma_f32_16x16x32_bf16 v[74:77], v[34:37], v[10:13], 0
	v_mfma_f32_16x16x32_bf16 v[78:81], v[42:45], v[10:13], 0
	v_mfma_f32_16x16x32_bf16 v[66:69], v[22:25], v[14:17], v[66:69]
	v_mfma_f32_16x16x32_bf16 v[70:73], v[30:33], v[14:17], v[70:73]
	v_mfma_f32_16x16x32_bf16 v[74:77], v[38:41], v[14:17], v[74:77]
	v_mfma_f32_16x16x32_bf16 v[78:81], v[46:49], v[14:17], v[78:81]
	ds_read_b64 v[184:185], v138 offset:36864
	ds_read_b64 v[186:187], v139 offset:36864
	ds_read_b64 v[188:189], v140 offset:36864
	ds_read_b64 v[190:191], v141 offset:36864
	ds_read_b64 v[192:193], v138 offset:38912
	ds_read_b64 v[194:195], v139 offset:38912
	ds_read_b64 v[196:197], v140 offset:38912
	ds_read_b64 v[198:199], v141 offset:38912
	s_nop 3
	v_max3_f32 v144, v50, v51, v52
	v_max3_f32 v145, v53, v54, v55
	v_max3_f32 v150, v56, v57, v58
	v_max3_f32 v151, v59, v60, v61
	v_max3_f32 v152, v62, v63, v64
	v_max3_f32 v144, v144, v145, v65
	v_max3_f32 v144, v144, v150, v151
	v_max_f32_e32 v144, v144, v152
	v_mov_b32_e32 v145, v144
	s_nop 1
	v_permlane16_swap_b32_e32 v144, v145
	v_max_f32_e32 v144, v144, v145
	v_mov_b32_e32 v145, v144
	s_nop 1
	v_permlane32_swap_b32_e32 v144, v145
	v_max_f32_e32 v144, v144, v145
	v_mul_f32_e32 v144, s100, v144
	v_max_f32_e32 v146, v132, v144
	v_cmp_gt_f32_e32 vcc, v146, v132
	s_cbranch_vccz .Lga_nors5
	v_sub_f32_e32 v148, v132, v146
	v_exp_f32_e32 v148, v148
	v_mov_b32_e32 v132, v146
	s_nop 0
	v_mul_f32_e32 v134, v134, v148
	v_pk_mul_f32 v[100:101], v[100:101], v[148:149] op_sel_hi:[1,0]
	v_pk_mul_f32 v[102:103], v[102:103], v[148:149] op_sel_hi:[1,0]
	v_pk_mul_f32 v[104:105], v[104:105], v[148:149] op_sel_hi:[1,0]
	v_pk_mul_f32 v[106:107], v[106:107], v[148:149] op_sel_hi:[1,0]
	v_pk_mul_f32 v[108:109], v[108:109], v[148:149] op_sel_hi:[1,0]
	v_pk_mul_f32 v[110:111], v[110:111], v[148:149] op_sel_hi:[1,0]
	v_pk_mul_f32 v[112:113], v[112:113], v[148:149] op_sel_hi:[1,0]
	v_pk_mul_f32 v[114:115], v[114:115], v[148:149] op_sel_hi:[1,0]

.Lga_nosw7:
	s_add_i32 m0, s32, 32768
	s_nop 0
	global_load_lds_dwordx4 v142, s[6:7]
	s_add_i32 m0, s41, 32768
	s_nop 0
	global_load_lds_dwordx4 v143, s[8:9]
	s_add_u32 s6, s6, 0xc0000
	s_addc_u32 s7, s7, 0
	s_add_u32 s8, s8, 0x80
	s_addc_u32 s9, s9, 0
	s_add_u32 s89, s89, 1
	s_branch .Lga_go3

.Lga_go3:
	ds_read_b128 v[18:21], v136 offset:49152
	ds_read_b128 v[22:25], v137 offset:49152
	ds_read_b128 v[26:29], v136 offset:51200
	ds_read_b128 v[30:33], v137 offset:51200
	ds_read_b128 v[34:37], v136 offset:53248
	ds_read_b128 v[38:41], v137 offset:53248
	ds_read_b128 v[42:45], v136 offset:55296
	ds_read_b128 v[46:49], v137 offset:55296
	s_waitcnt lgkmcnt(0)
	v_mfma_f32_16x16x32_bf16 v[50:53], v[18:21], v[2:5], 0
	v_mfma_f32_16x16x32_bf16 v[54:57], v[26:29], v[2:5], 0
	v_mfma_f32_16x16x32_bf16 v[58:61], v[34:37], v[2:5], 0
	v_mfma_f32_16x16x32_bf16 v[62:65], v[42:45], v[2:5], 0
	v_mfma_f32_16x16x32_bf16 v[50:53], v[22:25], v[6:9], v[50:53]
	v_mfma_f32_16x16x32_bf16 v[54:57], v[30:33], v[6:9], v[54:57]
	v_mfma_f32_16x16x32_bf16 v[58:61], v[38:41], v[6:9], v[58:61]
	v_mfma_f32_16x16x32_bf16 v[62:65], v[46:49], v[6:9], v[62:65]
	ds_read_b64 v[168:169], v138 offset:49152
	ds_read_b64 v[170:171], v139 offset:49152
	ds_read_b64 v[172:173], v140 offset:49152
	ds_read_b64 v[174:175], v141 offset:49152
	ds_read_b64 v[176:177], v138 offset:51200
	ds_read_b64 v[178:179], v139 offset:51200
	ds_read_b64 v[180:181], v140 offset:51200
	ds_read_b64 v[182:183], v141 offset:51200
	v_mfma_f32_16x16x32_bf16 v[66:69], v[18:21], v[10:13], 0
	v_mfma_f32_16x16x32_bf16 v[70:73], v[26:29], v[10:13], 0
	v_mfma_f32_16x16x32_bf16 v[74:77], v[34:37], v[10:13], 0
	v_mfma_f32_16x16x32_bf16 v[78:81], v[42:45], v[10:13], 0
	v_mfma_f32_16x16x32_bf16 v[66:69], v[22:25], v[14:17], v[66:69]
	v_mfma_f32_16x16x32_bf16 v[70:73], v[30:33], v[14:17], v[70:73]
	v_mfma_f32_16x16x32_bf16 v[74:77], v[38:41], v[14:17], v[74:77]
	v_mfma_f32_16x16x32_bf16 v[78:81], v[46:49], v[14:17], v[78:81]
	ds_read_b64 v[184:185], v138 offset:53248
	ds_read_b64 v[186:187], v139 offset:53248
	ds_read_b64 v[188:189], v140 offset:53248
	ds_read_b64 v[190:191], v141 offset:53248
	ds_read_b64 v[192:193], v138 offset:55296
	ds_read_b64 v[194:195], v139 offset:55296
	ds_read_b64 v[196:197], v140 offset:55296
	ds_read_b64 v[198:199], v141 offset:55296
	s_nop 3
	v_max3_f32 v144, v50, v51, v52
	v_max3_f32 v145, v53, v54, v55
	v_max3_f32 v150, v56, v57, v58
	v_max3_f32 v151, v59, v60, v61
	v_max3_f32 v152, v62, v63, v64
	v_max3_f32 v144, v144, v145, v65
	v_max3_f32 v144, v144, v150, v151
	v_max_f32_e32 v144, v144, v152
	v_mov_b32_e32 v145, v144
	s_nop 1
	v_permlane16_swap_b32_e32 v144, v145
	v_max_f32_e32 v144, v144, v145
	v_mov_b32_e32 v145, v144
	s_nop 1
	v_permlane32_swap_b32_e32 v144, v145
	v_max_f32_e32 v144, v144, v145
	v_mul_f32_e32 v144, s100, v144
	v_max_f32_e32 v146, v132, v144
	v_cmp_gt_f32_e32 vcc, v146, v132
	s_cbranch_vccz .Lga_nors7
	v_sub_f32_e32 v148, v132, v146
	v_exp_f32_e32 v148, v148
	v_mov_b32_e32 v132, v146
	s_nop 0
	v_mul_f32_e32 v134, v134, v148
	v_pk_mul_f32 v[100:101], v[100:101], v[148:149] op_sel_hi:[1,0]
	v_pk_mul_f32 v[102:103], v[102:103], v[148:149] op_sel_hi:[1,0]
	v_pk_mul_f32 v[104:105], v[104:105], v[148:149] op_sel_hi:[1,0]
	v_pk_mul_f32 v[106:107], v[106:107], v[148:149] op_sel_hi:[1,0]
	v_pk_mul_f32 v[108:109], v[108:109], v[148:149] op_sel_hi:[1,0]
	v_pk_mul_f32 v[110:111], v[110:111], v[148:149] op_sel_hi:[1,0]
	v_pk_mul_f32 v[112:113], v[112:113], v[148:149] op_sel_hi:[1,0]
	v_pk_mul_f32 v[114:115], v[114:115], v[148:149] op_sel_hi:[1,0]

.Lga_nors8:
	v_pk_fma_f32 v[66:67], v[66:67], v[86:87], v[146:147] op_sel_hi:[1,0,0] neg_lo:[0,0,1] neg_hi:[0,0,1]
	v_pk_fma_f32 v[68:69], v[68:69], v[86:87], v[146:147] op_sel_hi:[1,0,0] neg_lo:[0,0,1] neg_hi:[0,0,1]
	v_pk_fma_f32 v[70:71], v[70:71], v[86:87], v[146:147] op_sel_hi:[1,0,0] neg_lo:[0,0,1] neg_hi:[0,0,1]
	v_pk_fma_f32 v[72:73], v[72:73], v[86:87], v[146:147] op_sel_hi:[1,0,0] neg_lo:[0,0,1] neg_hi:[0,0,1]
	v_pk_fma_f32 v[74:75], v[74:75], v[86:87], v[146:147] op_sel_hi:[1,0,0] neg_lo:[0,0,1] neg_hi:[0,0,1]
	v_pk_fma_f32 v[76:77], v[76:77], v[86:87], v[146:147] op_sel_hi:[1,0,0] neg_lo:[0,0,1] neg_hi:[0,0,1]
	v_pk_fma_f32 v[78:79], v[78:79], v[86:87], v[146:147] op_sel_hi:[1,0,0] neg_lo:[0,0,1] neg_hi:[0,0,1]
	v_pk_fma_f32 v[80:81], v[80:81], v[86:87], v[146:147] op_sel_hi:[1,0,0] neg_lo:[0,0,1] neg_hi:[0,0,1]
	v_exp_f32_e32 v66, v66
	v_exp_f32_e32 v67, v67
	v_exp_f32_e32 v68, v68
	v_exp_f32_e32 v69, v69
	v_exp_f32_e32 v70, v70
	v_exp_f32_e32 v71, v71
	v_exp_f32_e32 v72, v72
	v_exp_f32_e32 v73, v73
	v_exp_f32_e32 v74, v74
	v_exp_f32_e32 v75, v75
	v_exp_f32_e32 v76, v76
	v_exp_f32_e32 v77, v77
	v_exp_f32_e32 v78, v78
	v_exp_f32_e32 v79, v79
	v_exp_f32_e32 v80, v80
	v_exp_f32_e32 v81, v81
	v_pk_add_f32 v[150:151], v[66:67], v[68:69]
	v_pk_add_f32 v[152:153], v[70:71], v[72:73]
	v_pk_add_f32 v[154:155], v[74:75], v[76:77]
	v_pk_add_f32 v[156:157], v[78:79], v[80:81]
	v_pk_add_f32 v[150:151], v[150:151], v[152:153]
	v_pk_add_f32 v[154:155], v[154:155], v[156:157]
	v_pk_add_f32 v[150:151], v[150:151], v[154:155]
	v_add_f32_e32 v150, v150, v151
	v_add_f32_e32 v135, v135, v150
	v_cvt_pk_bf16_f32 v208, v66, v67
	v_cvt_pk_bf16_f32 v209, v68, v69
	v_cvt_pk_bf16_f32 v210, v70, v71
	v_cvt_pk_bf16_f32 v211, v72, v73
	v_cvt_pk_bf16_f32 v212, v74, v75
	v_cvt_pk_bf16_f32 v213, v76, v77
	v_cvt_pk_bf16_f32 v214, v78, v79
	v_cvt_pk_bf16_f32 v215, v80, v81
	s_nop 1
	v_mfma_f32_16x16x32_bf16 v[116:119], v[168:171], v[208:211], v[116:119]
	v_mfma_f32_16x16x32_bf16 v[116:119], v[172:175], v[212:215], v[116:119]
	v_mfma_f32_16x16x32_bf16 v[120:123], v[176:179], v[208:211], v[120:123]
	v_mfma_f32_16x16x32_bf16 v[120:123], v[180:183], v[212:215], v[120:123]
	v_mfma_f32_16x16x32_bf16 v[124:127], v[184:187], v[208:211], v[124:127]
	v_mfma_f32_16x16x32_bf16 v[124:127], v[188:191], v[212:215], v[124:127]
	v_mfma_f32_16x16x32_bf16 v[128:131], v[192:195], v[208:211], v[128:131]
	v_mfma_f32_16x16x32_bf16 v[128:131], v[196:199], v[212:215], v[128:131]
	s_sub_u32 s42, s42, 1
	s_cmp_eq_u32 s42, 0
	s_cbranch_scc0 .Lga_loop
	s_nop 7
	s_nop 1
	v_mov_b32_e32 v145, v134
	s_nop 1
	v_permlane16_swap_b32_e32 v134, v145
	v_add_f32_e32 v134, v134, v145
	v_mov_b32_e32 v145, v134
	s_nop 1
	v_permlane32_swap_b32_e32 v134, v145
	v_add_f32_e32 v134, v134, v145
	v_rcp_f32_e32 v134, v134
	s_nop 0
	v_mul_f32_e32 v100, v100, v134
	v_mul_f32_e32 v101, v101, v134
	v_mul_f32_e32 v102, v102, v134
	v_mul_f32_e32 v103, v103, v134
	v_mul_f32_e32 v104, v104, v134
	v_mul_f32_e32 v105, v105, v134
	v_mul_f32_e32 v106, v106, v134
	v_mul_f32_e32 v107, v107, v134
	v_mul_f32_e32 v108, v108, v134
	v_mul_f32_e32 v109, v109, v134
	v_mul_f32_e32 v110, v110, v134
	v_mul_f32_e32 v111, v111, v134
	v_mul_f32_e32 v112, v112, v134
	v_mul_f32_e32 v113, v113, v134
	v_mul_f32_e32 v114, v114, v134
	v_mul_f32_e32 v115, v115, v134
	v_cvt_pk_bf16_f32 v146, v100, v101
	v_cvt_pk_bf16_f32 v147, v102, v103
	v_cvt_pk_bf16_f32 v148, v104, v105
	v_cvt_pk_bf16_f32 v149, v106, v107
	v_cvt_pk_bf16_f32 v150, v108, v109
	v_cvt_pk_bf16_f32 v151, v110, v111
	v_cvt_pk_bf16_f32 v152, v112, v113
	v_cvt_pk_bf16_f32 v153, v114, v115
	global_store_dwordx2 v[84:85], v[146:147], off offset:0
	global_store_dwordx2 v[84:85], v[148:149], off offset:32
	global_store_dwordx2 v[84:85], v[150:151], off offset:64
	global_store_dwordx2 v[84:85], v[152:153], off offset:96
	v_mov_b32_e32 v145, v135
	s_nop 1
	v_permlane16_swap_b32_e32 v135, v145
	v_add_f32_e32 v135, v135, v145
	v_mov_b32_e32 v145, v135
	s_nop 1
	v_permlane32_swap_b32_e32 v135, v145
	v_add_f32_e32 v135, v135, v145
	v_rcp_f32_e32 v135, v135
	s_nop 0
	v_mul_f32_e32 v116, v116, v135
	v_mul_f32_e32 v117, v117, v135
	v_mul_f32_e32 v118, v118, v135
	v_mul_f32_e32 v119, v119, v135
	v_mul_f32_e32 v120, v120, v135
	v_mul_f32_e32 v121, v121, v135
	v_mul_f32_e32 v122, v122, v135
	v_mul_f32_e32 v123, v123, v135
	v_mul_f32_e32 v124, v124, v135
	v_mul_f32_e32 v125, v125, v135
	v_mul_f32_e32 v126, v126, v135
	v_mul_f32_e32 v127, v127, v135
	v_mul_f32_e32 v128, v128, v135
	v_mul_f32_e32 v129, v129, v135
	v_mul_f32_e32 v130, v130, v135
	v_mul_f32_e32 v131, v131, v135
	v_cvt_pk_bf16_f32 v146, v116, v117
	v_cvt_pk_bf16_f32 v147, v118, v119
	v_cvt_pk_bf16_f32 v148, v120, v121
	v_cvt_pk_bf16_f32 v149, v122, v123
	v_cvt_pk_bf16_f32 v150, v124, v125
	v_cvt_pk_bf16_f32 v151, v126, v127
	v_cvt_pk_bf16_f32 v152, v128, v129
	v_cvt_pk_bf16_f32 v153, v130, v131
	global_store_dwordx2 v[84:85], v[146:147], off offset:128
	global_store_dwordx2 v[84:85], v[148:149], off offset:160
	global_store_dwordx2 v[84:85], v[150:151], off offset:192
	global_store_dwordx2 v[84:85], v[152:153], off offset:224
	s_add_u32 s1, s1, 0x70
	s_cmpk_lt_u32 s1, 0x100
	s_cbranch_scc1 .Lga_unit
	s_branch .LBB0_979
